# direct HBM->LDS (LDS-DMA) for the attention K tile: global_load_lds with the bank swizzle applied to the per-lane source address; the 2 K ds_write_b128 per wave per tile removed
# speedup vs baseline: 1.0034x; 1.0034x over previous
.LBB0_561:
	ds_read_b128 v[64:67], v189 offset:49152
	ds_read_b128 v[68:71], v189 offset:57344
	ds_read_b128 v[210:213], v190 offset:49152
	ds_read_b128 v[218:221], v190 offset:57344
	s_add_i32 s0, 0, 0x12000
	v_add_f32_e32 v148, 0, v175
	s_waitcnt lgkmcnt(3)
	v_mfma_f32_32x32x16_bf16 v[80:95], v[64:67], v[120:123], 0
	v_add_f32_e32 v148, v217, v148
	v_add_f32_e32 v148, v149, v148
	v_add_f32_e32 v148, v216, v148
	v_add_f32_e32 v148, v150, v148
	v_add_f32_e32 v148, v174, v148
	v_add_f32_e32 v148, v151, v148
	v_add_f32_e32 v148, v173, v148
	s_waitcnt lgkmcnt(2)
	v_mfma_f32_32x32x16_bf16 v[64:79], v[68:71], v[120:123], 0
	v_add_f32_e32 v148, v154, v148
	v_add_f32_e32 v148, v172, v148
	v_add_f32_e32 v148, v153, v148
	v_add_f32_e32 v148, v155, v148
	v_exp_f32_e32 v140, v140
	v_add_f32_e32 v148, v145, v148
	v_exp_f32_e32 v141, v141
	s_waitcnt lgkmcnt(1)
	v_mfma_f32_32x32x16_bf16 v[80:95], v[210:213], v[124:127], v[80:95]
	v_add_f32_e32 v148, v147, v148
	v_exp_f32_e32 v138, v138
	v_add_f32_e32 v148, v144, v148
	v_exp_f32_e32 v139, v139
	v_add_f32_e32 v148, v146, v148
	v_exp_f32_e32 v132, v132
	v_add_f32_e32 v148, v140, v148
	s_waitcnt lgkmcnt(0)
	v_mfma_f32_32x32x16_bf16 v[64:79], v[218:221], v[124:127], v[64:79]
	ds_read_b128 v[210:213], v191 offset:49152
	ds_read_b128 v[218:221], v191 offset:57344
	v_exp_f32_e32 v133, v133
	v_add_f32_e32 v148, v141, v148
	v_exp_f32_e32 v130, v130
	v_add_f32_e32 v148, v138, v148
	v_exp_f32_e32 v131, v131
	v_add_f32_e32 v148, v139, v148
	s_waitcnt lgkmcnt(1)
	v_mfma_f32_32x32x16_bf16 v[80:95], v[210:213], v[116:119], v[80:95]
	v_exp_f32_e32 v128, v128
	v_add_f32_e32 v148, v132, v148
	v_exp_f32_e32 v129, v129
	v_add_f32_e32 v148, v133, v148
	v_exp_f32_e32 v142, v142
	v_add_f32_e32 v148, v130, v148
	v_exp_f32_e32 v143, v143
	s_waitcnt lgkmcnt(0)
	v_mfma_f32_32x32x16_bf16 v[64:79], v[218:221], v[116:119], v[64:79]
	ds_read_b128 v[210:213], v192 offset:49152
	ds_read_b128 v[218:221], v192 offset:57344
	v_add_f32_e32 v148, v131, v148
	v_exp_f32_e32 v136, v136
	v_add_f32_e32 v148, v128, v148
	v_exp_f32_e32 v137, v137
	v_add_f32_e32 v148, v129, v148
	v_exp_f32_e32 v134, v134
	s_waitcnt lgkmcnt(1)
	v_mfma_f32_32x32x16_bf16 v[80:95], v[210:213], v[112:115], v[80:95]
	v_add_f32_e32 v148, v142, v148
	v_exp_f32_e32 v135, v135
	v_add_f32_e32 v148, v143, v148
	v_add_f32_e32 v148, v136, v148
	v_add_f32_e32 v148, v137, v148
	v_add_f32_e32 v148, v134, v148
	s_waitcnt lgkmcnt(0)
	v_mfma_f32_32x32x16_bf16 v[64:79], v[218:221], v[112:115], v[64:79]
	ds_read_b128 v[210:213], v193 offset:49152
	ds_read_b128 v[218:221], v193 offset:57344
	ds_read_b128 v[232:235], v194 offset:49152
	ds_read_b128 v[236:239], v194 offset:57344
	s_waitcnt lgkmcnt(3)
	v_mfma_f32_32x32x16_bf16 v[80:95], v[210:213], v[108:111], v[80:95]
	s_waitcnt lgkmcnt(2)
	v_mfma_f32_32x32x16_bf16 v[64:79], v[218:221], v[108:111], v[64:79]
	ds_read_b128 v[210:213], v195 offset:49152
	ds_read_b128 v[218:221], v195 offset:57344
	s_waitcnt lgkmcnt(3)
	v_mfma_f32_32x32x16_bf16 v[80:95], v[232:235], v[104:107], v[80:95]
	s_waitcnt lgkmcnt(2)
	v_mfma_f32_32x32x16_bf16 v[64:79], v[236:239], v[104:107], v[64:79]
	ds_read_b128 v[232:235], v196 offset:49152
	ds_read_b128 v[236:239], v196 offset:57344
	s_waitcnt lgkmcnt(3)
	v_mfma_f32_32x32x16_bf16 v[80:95], v[210:213], v[100:103], v[80:95]
	v_add_u32_e32 v230, s0, v198
	v_add_u32_e32 v231, s0, v200
	s_waitcnt lgkmcnt(2)
	v_mfma_f32_32x32x16_bf16 v[64:79], v[218:221], v[100:103], v[64:79]
	ds_read_b128 v[210:213], v230
	ds_read_b128 v[218:221], v230 offset:4096
	ds_read_b128 v[222:225], v197
	s_waitcnt lgkmcnt(4)
	v_mfma_f32_32x32x16_bf16 v[80:95], v[232:235], v[96:99], v[80:95]
	s_waitcnt lgkmcnt(3)
	v_mfma_f32_32x32x16_bf16 v[64:79], v[236:239], v[96:99], v[64:79]
	ds_read_b128 v[232:235], v231
	ds_read_b128 v[236:239], v231 offset:4096
	ds_read_b128 v[226:229], v184
	s_waitcnt lgkmcnt(3)
	v_mfma_f32_32x32x16_bf16 v[80:95], v[210:213], v[222:225], v[80:95]
	v_mfma_f32_32x32x16_bf16 v[64:79], v[218:221], v[222:225], v[64:79]
	v_add_u32_e32 v244, s0, v202
	v_add_u32_e32 v247, s0, v204
	ds_read_b128 v[210:213], v244
	ds_read_b128 v[218:221], v244 offset:4096
	ds_read_b128 v[222:225], v183
	s_waitcnt lgkmcnt(3)
	v_mfma_f32_32x32x16_bf16 v[80:95], v[232:235], v[226:229], v[80:95]
	v_add_f32_e32 v214, v135, v148
	v_mov_b32_e32 v215, v214
	s_nop 1
	v_permlane32_swap_b32_e32 v214, v215
	v_mfma_f32_32x32x16_bf16 v[64:79], v[236:239], v[226:229], v[64:79]
	ds_read_b128 v[232:235], v247
	ds_read_b128 v[236:239], v247 offset:4096
	ds_read_b128 v[226:229], v182
	s_waitcnt lgkmcnt(3)
	v_mfma_f32_32x32x16_bf16 v[80:95], v[210:213], v[222:225], v[80:95]
	v_mfma_f32_32x32x16_bf16 v[64:79], v[218:221], v[222:225], v[64:79]
	v_cvt_pk_bf16_f32 v148, v175, v217
	v_cvt_pk_bf16_f32 v149, v149, v216
	v_cvt_pk_bf16_f32 v150, v150, v174
	v_cvt_pk_bf16_f32 v151, v151, v173
	v_cvt_pk_bf16_f32 v152, v154, v172
	v_cvt_pk_bf16_f32 v153, v153, v155
	s_waitcnt lgkmcnt(0)
	v_mfma_f32_32x32x16_bf16 v[80:95], v[232:235], v[226:229], v[80:95]
	v_cvt_pk_bf16_f32 v154, v145, v147
	v_permlane32_swap_b32_e32 v148, v150
	v_cvt_pk_bf16_f32 v155, v144, v146
	v_permlane32_swap_b32_e32 v152, v154
	v_cvt_pk_bf16_f32 v216, v140, v141
	v_mfma_f32_32x32x16_bf16 v[64:79], v[236:239], v[226:229], v[64:79]
	v_cvt_pk_bf16_f32 v217, v138, v139
	v_cvt_pk_bf16_f32 v218, v132, v133
	v_cvt_pk_bf16_f32 v219, v130, v131
	v_cvt_pk_bf16_f32 v220, v128, v129
	v_cvt_pk_bf16_f32 v221, v142, v143
	v_cvt_pk_bf16_f32 v222, v136, v137
	v_cvt_pk_bf16_f32 v223, v134, v135
	v_permlane32_swap_b32_e32 v149, v151
	v_permlane32_swap_b32_e32 v153, v155
	v_permlane32_swap_b32_e32 v216, v218
	v_permlane32_swap_b32_e32 v217, v219
	v_permlane32_swap_b32_e32 v220, v222
	v_permlane32_swap_b32_e32 v221, v223
	v_lshl_add_u64 v[172:173], s[64:65], 0, v[158:159]
	s_mov_b32 s0, 0x34e80000
	v_add_co_u32_e32 v132, vcc, s0, v172
	s_mov_b32 s0, 0x34ea0000
	s_nop 0
	v_addc_co_u32_e32 v133, vcc, 0, v173, vcc
	v_add_co_u32_e32 v136, vcc, s0, v172
	v_lshl_add_u64 v[174:175], s[64:65], 0, v[170:171]
	s_nop 0
	v_addc_co_u32_e32 v137, vcc, 0, v173, vcc
	global_load_dwordx4 v[128:131], v[132:133], off offset:256
	s_nop 0
	v_xor_b32_e32 v134, v243, v132
	v_mov_b32_e32 v135, v133
	s_lshl_b32 s100, s33, 4
	s_add_i32 m0, s100, 0x8000
	s_nop 0
	global_load_lds_dwordx4 v[134:135], off
	s_nop 0
	global_load_dwordx4 v[140:143], v[136:137], off offset:256
	s_nop 0
	v_xor_b32_e32 v138, v243, v136
	v_mov_b32_e32 v139, v137
	s_add_i32 m0, s100, 0xa000
	s_nop 0
	global_load_lds_dwordx4 v[138:139], off
	s_mov_b32 s0, 0x1ea04000
	v_add_co_u32_e32 v144, vcc, s0, v174
	s_nop 1
	v_addc_co_u32_e32 v145, vcc, 0, v175, vcc
	global_load_dwordx4 v[144:147], v[144:145], off
	ds_read_b64_tr_b16 v[224:225], v181 offset:0
	ds_read_b64_tr_b16 v[226:227], v181 offset:0x800
	ds_read_b64_tr_b16 v[228:229], v181 offset:0x1000
	ds_read_b64_tr_b16 v[230:231], v181 offset:0x1800
	ds_read_b64_tr_b16 v[232:233], v181 offset:0x2000
	ds_read_b64_tr_b16 v[234:235], v181 offset:0x2800
	ds_read_b64_tr_b16 v[236:237], v181 offset:0x3000
	ds_read_b64_tr_b16 v[238:239], v181 offset:0x3800
	s_nop 0
	s_waitcnt lgkmcnt(6)
	v_mfma_f32_32x32x16_bf16 v[0:15], v[148:151], v[224:227], v[0:15]
	ds_read_b64_tr_b16 v[224:225], v181 offset:0x200
	ds_read_b64_tr_b16 v[226:227], v181 offset:0xa00
	s_waitcnt lgkmcnt(6)
	v_mfma_f32_32x32x16_bf16 v[0:15], v[152:155], v[228:231], v[0:15]
	ds_read_b64_tr_b16 v[228:229], v181 offset:0x1200
	ds_read_b64_tr_b16 v[230:231], v181 offset:0x1a00
	s_waitcnt lgkmcnt(6)
	v_mfma_f32_32x32x16_bf16 v[0:15], v[216:219], v[232:235], v[0:15]
	ds_read_b64_tr_b16 v[232:233], v181 offset:0x2200
	ds_read_b64_tr_b16 v[234:235], v181 offset:0x2a00
	s_waitcnt lgkmcnt(6)
	v_mfma_f32_32x32x16_bf16 v[0:15], v[220:223], v[236:239], v[0:15]
	ds_read_b64_tr_b16 v[236:237], v181 offset:0x3200
	ds_read_b64_tr_b16 v[238:239], v181 offset:0x3a00
	s_waitcnt lgkmcnt(6)
	v_mfma_f32_32x32x16_bf16 v[48:63], v[148:151], v[224:227], v[48:63]
	ds_read_b64_tr_b16 v[224:225], v181 offset:0x400
	ds_read_b64_tr_b16 v[226:227], v181 offset:0xc00
	s_waitcnt lgkmcnt(6)
	v_mfma_f32_32x32x16_bf16 v[48:63], v[152:155], v[228:231], v[48:63]
	ds_read_b64_tr_b16 v[228:229], v181 offset:0x1400
	ds_read_b64_tr_b16 v[230:231], v181 offset:0x1c00
	s_waitcnt lgkmcnt(6)
	v_mfma_f32_32x32x16_bf16 v[48:63], v[216:219], v[232:235], v[48:63]
	ds_read_b64_tr_b16 v[232:233], v181 offset:0x2400
	ds_read_b64_tr_b16 v[234:235], v181 offset:0x2c00
	s_waitcnt lgkmcnt(6)
	v_mfma_f32_32x32x16_bf16 v[48:63], v[220:223], v[236:239], v[48:63]
	ds_read_b64_tr_b16 v[236:237], v181 offset:0x3400
	ds_read_b64_tr_b16 v[238:239], v181 offset:0x3c00
	s_waitcnt lgkmcnt(6)
	v_mfma_f32_32x32x16_bf16 v[32:47], v[148:151], v[224:227], v[32:47]
	ds_read_b64_tr_b16 v[224:225], v181 offset:0x600
	ds_read_b64_tr_b16 v[226:227], v181 offset:0xe00
	s_waitcnt lgkmcnt(6)
	v_mfma_f32_32x32x16_bf16 v[32:47], v[152:155], v[228:231], v[32:47]
	ds_read_b64_tr_b16 v[228:229], v181 offset:0x1600
	ds_read_b64_tr_b16 v[230:231], v181 offset:0x1e00
	s_waitcnt lgkmcnt(6)
	v_mfma_f32_32x32x16_bf16 v[32:47], v[216:219], v[232:235], v[32:47]
	ds_read_b64_tr_b16 v[232:233], v181 offset:0x2600
	ds_read_b64_tr_b16 v[234:235], v181 offset:0x2e00
	s_waitcnt lgkmcnt(6)
	v_mfma_f32_32x32x16_bf16 v[32:47], v[220:223], v[236:239], v[32:47]
	ds_read_b64_tr_b16 v[236:237], v181 offset:0x3600
	ds_read_b64_tr_b16 v[238:239], v181 offset:0x3e00
	s_waitcnt lgkmcnt(6)
	v_mfma_f32_32x32x16_bf16 v[16:31], v[148:151], v[224:227], v[16:31]
	v_max_f32_e32 v148, v81, v81
	v_max_f32_e32 v149, v80, v80
	v_max_f32_e32 v148, v149, v148
	v_max3_f32 v148, v148, v82, v83
	v_max3_f32 v148, v148, v84, v85
	v_max3_f32 v148, v148, v86, v87
	v_max3_f32 v148, v148, v88, v89
	v_max3_f32 v148, v148, v90, v91
	v_max3_f32 v148, v148, v92, v93
	s_waitcnt lgkmcnt(4)
	v_mfma_f32_32x32x16_bf16 v[16:31], v[152:155], v[228:231], v[16:31]
	v_max3_f32 v148, v148, v94, v95
	v_max3_f32 v148, v148, v64, v65
	v_max3_f32 v148, v148, v66, v67
	v_max3_f32 v148, v148, v68, v69
	v_max3_f32 v148, v148, v70, v71
	v_max3_f32 v148, v148, v72, v73
	v_max3_f32 v148, v148, v74, v75
	v_max3_f32 v148, v148, v76, v77
	s_waitcnt lgkmcnt(2)
	v_mfma_f32_32x32x16_bf16 v[16:31], v[216:219], v[232:235], v[16:31]
	v_max3_f32 v148, v148, v78, v79
	v_mov_b32_e32 v149, v148
	s_nop 1
	v_permlane32_swap_b32_e32 v148, v149
	v_max_f32_e32 v149, v149, v149
	v_max_f32_e32 v148, v148, v148
	v_max_f32_e32 v148, v148, v149
	v_sub_f32_e32 v149, v148, v209
	v_cmp_ge_f32_e32 vcc, s90, v149
	v_max_f32_e32 v149, v209, v209
	v_max_f32_e32 v148, v149, v148
	s_waitcnt lgkmcnt(0)
	v_mfma_f32_32x32x16_bf16 v[16:31], v[220:223], v[236:239], v[16:31]
	v_sub_f32_e32 v149, v209, v148
	v_mul_f32_e32 v149, 0x3dd53b94, v149
	v_exp_f32_e32 v149, v149
	s_cmp_eq_u64 vcc, exec
	s_cselect_b64 s[6:7], -1, 0
	s_barrier
	s_waitcnt vmcnt(0)
	v_cndmask_b32_e64 v152, v149, 1.0, s[6:7]
	s_waitcnt vmcnt(4)
	ds_write_b128 v185, v[128:131]
	s_waitcnt vmcnt(2)
	ds_write_b128 v186, v[140:143]
	s_waitcnt vmcnt(1)
	v_add_u32_e32 v128, 0x10000, v207
	v_cmp_gt_f32_e32 vcc, 1.0, v152
	s_waitcnt vmcnt(0)
	ds_write_b128 v128, v[144:147]
	s_cbranch_vccz .LBB0_565
	s_and_saveexec_b64 s[0:1], s[4:5]
	ds_write_b32 v178, v152 offset:128
	s_or_b64 exec, exec, s[0:1]
	s_waitcnt lgkmcnt(0)
	v_add_u32_e32 v140, v157, v160
	ds_read_b128 v[128:131], v140 offset:224
	ds_read_b128 v[132:135], v140 offset:192
	ds_read_b128 v[136:139], v140 offset:160
	ds_read_b128 v[140:143], v140 offset:128
	s_waitcnt lgkmcnt(3)
	v_pk_mul_f32 v[12:13], v[12:13], v[128:129]
	s_waitcnt lgkmcnt(2)
	v_pk_mul_f32 v[8:9], v[8:9], v[132:133]
	s_waitcnt lgkmcnt(1)
	v_pk_mul_f32 v[4:5], v[4:5], v[136:137]
	v_pk_mul_f32 v[14:15], v[14:15], v[130:131]
	v_pk_mul_f32 v[10:11], v[10:11], v[134:135]
	v_pk_mul_f32 v[6:7], v[6:7], v[138:139]
	s_waitcnt lgkmcnt(0)
	v_pk_mul_f32 v[2:3], v[2:3], v[142:143]
	v_pk_mul_f32 v[0:1], v[0:1], v[140:141]
	v_pk_mul_f32 v[60:61], v[60:61], v[128:129]
	v_pk_mul_f32 v[56:57], v[56:57], v[132:133]
	v_pk_mul_f32 v[52:53], v[52:53], v[136:137]
	v_pk_mul_f32 v[62:63], v[62:63], v[130:131]
	v_pk_mul_f32 v[58:59], v[58:59], v[134:135]
	v_pk_mul_f32 v[54:55], v[54:55], v[138:139]
	v_pk_mul_f32 v[50:51], v[50:51], v[142:143]
	v_pk_mul_f32 v[48:49], v[48:49], v[140:141]
	v_pk_mul_f32 v[44:45], v[44:45], v[128:129]
	v_pk_mul_f32 v[40:41], v[40:41], v[132:133]
	v_pk_mul_f32 v[36:37], v[36:37], v[136:137]
	v_pk_mul_f32 v[46:47], v[46:47], v[130:131]
	v_pk_mul_f32 v[42:43], v[42:43], v[134:135]
	v_pk_mul_f32 v[38:39], v[38:39], v[138:139]
	v_pk_mul_f32 v[34:35], v[34:35], v[142:143]
	v_pk_mul_f32 v[32:33], v[32:33], v[140:141]
	v_pk_mul_f32 v[28:29], v[28:29], v[128:129]
	v_pk_mul_f32 v[24:25], v[24:25], v[132:133]
	v_pk_mul_f32 v[20:21], v[20:21], v[136:137]
	v_pk_mul_f32 v[30:31], v[30:31], v[130:131]
	v_pk_mul_f32 v[26:27], v[26:27], v[134:135]
	v_pk_mul_f32 v[22:23], v[22:23], v[138:139]
	v_pk_mul_f32 v[18:19], v[18:19], v[142:143]
	v_pk_mul_f32 v[16:17], v[16:17], v[140:141]
.LBB0_565:
	v_cndmask_b32_e64 v153, v148, v209, s[6:7]
	v_mul_f32_e32 v144, 0xbdd53b94, v153
	v_fmamk_f32 v80, v80, 0x3dd53b94, v144
	v_fmamk_f32 v81, v81, 0x3dd53b94, v144
	v_fmamk_f32 v82, v82, 0x3dd53b94, v144
	v_fmamk_f32 v83, v83, 0x3dd53b94, v144
	v_fmamk_f32 v84, v84, 0x3dd53b94, v144
	v_fmamk_f32 v85, v85, 0x3dd53b94, v144
	v_fmamk_f32 v86, v86, 0x3dd53b94, v144
	v_fmamk_f32 v87, v87, 0x3dd53b94, v144
	v_fmamk_f32 v88, v88, 0x3dd53b94, v144
	v_fmamk_f32 v89, v89, 0x3dd53b94, v144
	v_fmamk_f32 v90, v90, 0x3dd53b94, v144
	v_fmamk_f32 v91, v91, 0x3dd53b94, v144
	v_fmamk_f32 v92, v92, 0x3dd53b94, v144
	v_fmamk_f32 v93, v93, 0x3dd53b94, v144
	v_fmamk_f32 v94, v94, 0x3dd53b94, v144
	v_fmamk_f32 v95, v95, 0x3dd53b94, v144
	v_fmamk_f32 v218, v68, 0x3dd53b94, v144
	v_fmamk_f32 v148, v71, 0x3dd53b94, v144
	v_fmamk_f32 v149, v72, 0x3dd53b94, v144
	v_fmamk_f32 v219, v77, 0x3dd53b94, v144
	v_fmamk_f32 v155, v64, 0x3dd53b94, v144
	v_fmamk_f32 v209, v65, 0x3dd53b94, v144
	v_fmamk_f32 v216, v66, 0x3dd53b94, v144
	v_fmamk_f32 v217, v67, 0x3dd53b94, v144
	v_fmamk_f32 v146, v69, 0x3dd53b94, v144
	v_fmamk_f32 v147, v70, 0x3dd53b94, v144
	v_fmamk_f32 v150, v73, 0x3dd53b94, v144
	v_fmamk_f32 v151, v74, 0x3dd53b94, v144
	v_fmamk_f32 v154, v75, 0x3dd53b94, v144
	v_fmamk_f32 v145, v76, 0x3dd53b94, v144
	v_exp_f32_e32 v141, v80
	v_exp_f32_e32 v143, v81
	v_exp_f32_e32 v139, v82
	v_exp_f32_e32 v142, v83
	v_exp_f32_e32 v138, v84
	v_exp_f32_e32 v140, v85
	v_exp_f32_e32 v136, v86
	v_exp_f32_e32 v137, v87
	v_exp_f32_e32 v133, v88
	v_exp_f32_e32 v135, v89
	v_exp_f32_e32 v132, v90
	v_exp_f32_e32 v134, v91
	v_exp_f32_e32 v129, v92
	v_exp_f32_e32 v131, v93
	v_exp_f32_e32 v128, v94
	v_exp_f32_e32 v130, v95
	v_fmamk_f32 v220, v78, 0x3dd53b94, v144
	v_fmac_f32_e32 v144, 0x3dd53b94, v79
	s_waitcnt lgkmcnt(0)
	s_barrier
	ds_read_b128 v[64:67], v189 offset:32768
	ds_read_b128 v[68:71], v189 offset:40960
	ds_read_b128 v[222:225], v190 offset:32768
	ds_read_b128 v[226:229], v190 offset:40960
	v_exp_f32_e32 v155, v155
	v_exp_f32_e32 v209, v209
	s_waitcnt lgkmcnt(3)
	v_mfma_f32_32x32x16_bf16 v[80:95], v[64:67], v[120:123], 0
	v_exp_f32_e32 v216, v216
	v_exp_f32_e32 v217, v217
	s_waitcnt lgkmcnt(2)
	v_mfma_f32_32x32x16_bf16 v[64:79], v[68:71], v[120:123], 0
	v_add_f32_e32 v240, 0, v141
	v_add_f32_e32 v240, v143, v240
	s_waitcnt lgkmcnt(0)
	v_mfma_f32_32x32x16_bf16 v[64:79], v[226:229], v[124:127], v[64:79]
	v_add_f32_e32 v240, v139, v240
	v_add_f32_e32 v240, v142, v240
	v_mfma_f32_32x32x16_bf16 v[80:95], v[222:225], v[124:127], v[80:95]
	v_exp_f32_e32 v146, v146
	v_add_f32_e32 v240, v138, v240
	ds_read_b128 v[222:225], v191 offset:32768
	ds_read_b128 v[226:229], v191 offset:40960
	s_waitcnt lgkmcnt(0)
	v_mfma_f32_32x32x16_bf16 v[64:79], v[226:229], v[116:119], v[64:79]
	v_add_f32_e32 v240, v140, v240
	v_exp_f32_e32 v147, v147
	v_mfma_f32_32x32x16_bf16 v[80:95], v[222:225], v[116:119], v[80:95]
	v_add_f32_e32 v240, v136, v240
	v_add_f32_e32 v240, v137, v240
	ds_read_b128 v[222:225], v192 offset:32768
	ds_read_b128 v[226:229], v192 offset:40960
	s_waitcnt lgkmcnt(0)
	v_mfma_f32_32x32x16_bf16 v[64:79], v[226:229], v[112:115], v[64:79]
	v_exp_f32_e32 v154, v154
	v_add_f32_e32 v240, v133, v240
	v_mfma_f32_32x32x16_bf16 v[80:95], v[222:225], v[112:115], v[80:95]
	v_add_f32_e32 v240, v135, v240
	v_exp_f32_e32 v145, v145
	ds_read_b128 v[222:225], v193 offset:32768
	ds_read_b128 v[226:229], v193 offset:40960
	s_waitcnt lgkmcnt(0)
	v_mfma_f32_32x32x16_bf16 v[64:79], v[226:229], v[108:111], v[64:79]
	v_add_f32_e32 v240, v132, v240
	v_add_f32_e32 v240, v134, v240
	v_mfma_f32_32x32x16_bf16 v[80:95], v[222:225], v[108:111], v[80:95]
	v_exp_f32_e32 v144, v144
	v_add_f32_e32 v240, v129, v240
	ds_read_b128 v[222:225], v194 offset:32768
	ds_read_b128 v[226:229], v194 offset:40960
	s_waitcnt lgkmcnt(0)
	v_mfma_f32_32x32x16_bf16 v[64:79], v[226:229], v[104:107], v[64:79]
	v_add_f32_e32 v240, v131, v240
	v_exp_f32_e32 v218, v218
	v_mfma_f32_32x32x16_bf16 v[80:95], v[222:225], v[104:107], v[80:95]
	v_add_f32_e32 v240, v128, v240
	v_add_f32_e32 v240, v130, v240
	ds_read_b128 v[222:225], v195 offset:32768
	ds_read_b128 v[226:229], v195 offset:40960
	s_waitcnt lgkmcnt(0)
	v_mfma_f32_32x32x16_bf16 v[64:79], v[226:229], v[100:103], v[64:79]
	v_exp_f32_e32 v148, v148
	v_add_f32_e32 v240, v155, v240
	v_mfma_f32_32x32x16_bf16 v[80:95], v[222:225], v[100:103], v[80:95]
	v_add_f32_e32 v240, v209, v240
	v_exp_f32_e32 v149, v149
	ds_read_b128 v[222:225], v196 offset:32768
	ds_read_b128 v[226:229], v196 offset:40960
	s_waitcnt lgkmcnt(0)
	v_mfma_f32_32x32x16_bf16 v[64:79], v[226:229], v[96:99], v[64:79]
	v_add_f32_e32 v240, v216, v240
	v_add_f32_e32 v240, v217, v240
	v_mfma_f32_32x32x16_bf16 v[80:95], v[222:225], v[96:99], v[80:95]
	v_exp_f32_e32 v150, v150
	v_add_f32_e32 v240, v218, v240
	ds_read_b128 v[222:225], v199
	ds_read_b128 v[226:229], v199 offset:4096
	ds_read_b128 v[230:233], v197
	s_waitcnt lgkmcnt(0)
	v_mfma_f32_32x32x16_bf16 v[64:79], v[226:229], v[230:233], v[64:79]
	v_add_f32_e32 v240, v146, v240
	v_exp_f32_e32 v151, v151
	v_mfma_f32_32x32x16_bf16 v[80:95], v[222:225], v[230:233], v[80:95]
	v_add_f32_e32 v240, v147, v240
	v_add_f32_e32 v240, v148, v240
	ds_read_b128 v[222:225], v201
	ds_read_b128 v[226:229], v201 offset:4096
	ds_read_b128 v[230:233], v184
	s_waitcnt lgkmcnt(0)
	v_mfma_f32_32x32x16_bf16 v[64:79], v[226:229], v[230:233], v[64:79]
	v_exp_f32_e32 v219, v219
	v_add_f32_e32 v240, v149, v240
	v_mfma_f32_32x32x16_bf16 v[80:95], v[222:225], v[230:233], v[80:95]
	v_add_f32_e32 v240, v150, v240
	v_exp_f32_e32 v220, v220
	ds_read_b128 v[222:225], v203
	ds_read_b128 v[226:229], v203 offset:4096
	ds_read_b128 v[230:233], v183
	s_waitcnt lgkmcnt(0)
	v_mfma_f32_32x32x16_bf16 v[64:79], v[226:229], v[230:233], v[64:79]
	v_add_f32_e32 v240, v151, v240
	v_add_f32_e32 v240, v154, v240
	v_mfma_f32_32x32x16_bf16 v[80:95], v[222:225], v[230:233], v[80:95]
	v_add_f32_e32 v240, v145, v240
	v_add_f32_e32 v240, v219, v240
	ds_read_b128 v[222:225], v205
	ds_read_b128 v[226:229], v205 offset:4096
	ds_read_b128 v[230:233], v182
	s_waitcnt lgkmcnt(0)
	v_mfma_f32_32x32x16_bf16 v[64:79], v[226:229], v[230:233], v[64:79]
	v_add_f32_e32 v240, v220, v240
	v_add_f32_e32 v240, v144, v240
	v_mfma_f32_32x32x16_bf16 v[80:95], v[222:225], v[230:233], v[80:95]
	v_cvt_pk_bf16_f32 v226, v218, v146
	v_cvt_pk_bf16_f32 v227, v147, v148
	v_cvt_pk_bf16_f32 v228, v149, v150
	v_cvt_pk_bf16_f32 v229, v151, v154
	v_cvt_pk_bf16_f32 v230, v145, v219
	v_cvt_pk_bf16_f32 v231, v220, v144
	v_mov_b32_e32 v218, v240
	v_mov_b32_e32 v219, v240
	v_cvt_pk_bf16_f32 v148, v141, v143
	v_cvt_pk_bf16_f32 v149, v139, v142
	v_cvt_pk_bf16_f32 v150, v138, v140
	v_cvt_pk_bf16_f32 v151, v136, v137
	v_permlane32_swap_b32_e32 v218, v219
	v_permlane32_swap_b32_e32 v148, v150
	v_permlane32_swap_b32_e32 v149, v151
	v_cvt_pk_bf16_f32 v220, v133, v135
	v_cvt_pk_bf16_f32 v221, v132, v134
	v_cvt_pk_bf16_f32 v222, v129, v131
	v_cvt_pk_bf16_f32 v223, v128, v130
	v_cvt_pk_bf16_f32 v224, v155, v209
	v_cvt_pk_bf16_f32 v225, v216, v217
	s_nop 0
	v_permlane32_swap_b32_e32 v220, v222
	v_permlane32_swap_b32_e32 v221, v223
	v_permlane32_swap_b32_e32 v224, v226
	v_permlane32_swap_b32_e32 v225, v227
	v_permlane32_swap_b32_e32 v228, v230
	v_permlane32_swap_b32_e32 v229, v231
	s_mov_b32 s0, 0x34ec0000
	v_add_co_u32_e32 v132, vcc, s0, v172
	s_mov_b32 s0, 0x34ee0000
	s_nop 0
	v_addc_co_u32_e32 v133, vcc, 0, v173, vcc
	v_add_co_u32_e32 v136, vcc, s0, v172
	s_mov_b32 s0, 0x1ea06000
	s_nop 0
	v_addc_co_u32_e32 v137, vcc, 0, v173, vcc
	global_load_dwordx4 v[128:131], v[132:133], off offset:256
	s_nop 0
	v_xor_b32_e32 v134, v243, v132
	v_mov_b32_e32 v135, v133
	s_lshl_b32 s100, s33, 4
	s_add_i32 m0, s100, 0xc000
	s_nop 0
	global_load_lds_dwordx4 v[134:135], off
	s_nop 0
	global_load_dwordx4 v[140:143], v[136:137], off offset:256
	s_nop 0
	v_xor_b32_e32 v138, v243, v136
	v_mov_b32_e32 v139, v137
	s_add_i32 m0, s100, 0xe000
	s_nop 0
	global_load_lds_dwordx4 v[138:139], off
	v_add_co_u32_e32 v144, vcc, s0, v174
	s_nop 1
	v_addc_co_u32_e32 v145, vcc, 0, v175, vcc
	global_load_dwordx4 v[144:147], v[144:145], off
	ds_read_b64_tr_b16 v[172:173], v180 offset:0
	ds_read_b64_tr_b16 v[174:175], v180 offset:0x800
	ds_read_b64_tr_b16 v[232:233], v180 offset:0x1000
	ds_read_b64_tr_b16 v[234:235], v180 offset:0x1800
	ds_read_b64_tr_b16 v[236:237], v180 offset:0x2000
	ds_read_b64_tr_b16 v[238:239], v180 offset:0x2800
	ds_read_b64_tr_b16 v[248:249], v180 offset:0x3000
	ds_read_b64_tr_b16 v[250:251], v180 offset:0x3800
	s_nop 0
	s_waitcnt lgkmcnt(6)
	v_mfma_f32_32x32x16_bf16 v[0:15], v[148:151], v[172:175], v[0:15]
	ds_read_b64_tr_b16 v[172:173], v180 offset:0x200
	ds_read_b64_tr_b16 v[174:175], v180 offset:0xa00
	s_waitcnt lgkmcnt(6)
	v_mfma_f32_32x32x16_bf16 v[0:15], v[220:223], v[232:235], v[0:15]
	ds_read_b64_tr_b16 v[232:233], v180 offset:0x1200
	ds_read_b64_tr_b16 v[234:235], v180 offset:0x1a00
	s_waitcnt lgkmcnt(6)
	v_mfma_f32_32x32x16_bf16 v[0:15], v[224:227], v[236:239], v[0:15]
	ds_read_b64_tr_b16 v[236:237], v180 offset:0x2200
	ds_read_b64_tr_b16 v[238:239], v180 offset:0x2a00
	s_waitcnt lgkmcnt(6)
	v_mfma_f32_32x32x16_bf16 v[0:15], v[228:231], v[248:251], v[0:15]
	ds_read_b64_tr_b16 v[248:249], v180 offset:0x3200
	ds_read_b64_tr_b16 v[250:251], v180 offset:0x3a00
	s_waitcnt lgkmcnt(6)
	v_mfma_f32_32x32x16_bf16 v[48:63], v[148:151], v[172:175], v[48:63]
	ds_read_b64_tr_b16 v[172:173], v180 offset:0x400
	ds_read_b64_tr_b16 v[174:175], v180 offset:0xc00
	s_waitcnt lgkmcnt(6)
	v_mfma_f32_32x32x16_bf16 v[48:63], v[220:223], v[232:235], v[48:63]
	ds_read_b64_tr_b16 v[232:233], v180 offset:0x1400
	ds_read_b64_tr_b16 v[234:235], v180 offset:0x1c00
	s_waitcnt lgkmcnt(6)
	v_mfma_f32_32x32x16_bf16 v[48:63], v[224:227], v[236:239], v[48:63]
	ds_read_b64_tr_b16 v[236:237], v180 offset:0x2400
	ds_read_b64_tr_b16 v[238:239], v180 offset:0x2c00
	s_waitcnt lgkmcnt(6)
	v_mfma_f32_32x32x16_bf16 v[48:63], v[228:231], v[248:251], v[48:63]
	ds_read_b64_tr_b16 v[248:249], v180 offset:0x3400
	ds_read_b64_tr_b16 v[250:251], v180 offset:0x3c00
	s_waitcnt lgkmcnt(6)
	v_mfma_f32_32x32x16_bf16 v[32:47], v[148:151], v[172:175], v[32:47]
	ds_read_b64_tr_b16 v[172:173], v180 offset:0x600
	ds_read_b64_tr_b16 v[174:175], v180 offset:0xe00
	s_waitcnt lgkmcnt(6)
	v_mfma_f32_32x32x16_bf16 v[32:47], v[220:223], v[232:235], v[32:47]
	ds_read_b64_tr_b16 v[232:233], v180 offset:0x1600
	ds_read_b64_tr_b16 v[234:235], v180 offset:0x1e00
	s_waitcnt lgkmcnt(6)
	v_mfma_f32_32x32x16_bf16 v[32:47], v[224:227], v[236:239], v[32:47]
	ds_read_b64_tr_b16 v[236:237], v180 offset:0x2600
	ds_read_b64_tr_b16 v[238:239], v180 offset:0x2e00
	s_waitcnt lgkmcnt(6)
	v_mfma_f32_32x32x16_bf16 v[32:47], v[228:231], v[248:251], v[32:47]
	ds_read_b64_tr_b16 v[248:249], v180 offset:0x3600
	ds_read_b64_tr_b16 v[250:251], v180 offset:0x3e00
	s_waitcnt lgkmcnt(6)
	v_mfma_f32_32x32x16_bf16 v[16:31], v[148:151], v[172:175], v[16:31]
	v_max_f32_e32 v148, v81, v81
	v_max_f32_e32 v149, v80, v80
	v_max_f32_e32 v148, v149, v148
	v_max3_f32 v148, v148, v82, v83
	v_max3_f32 v148, v148, v84, v85
	v_max3_f32 v148, v148, v86, v87
	v_max3_f32 v148, v148, v88, v89
	v_max3_f32 v148, v148, v90, v91
	v_max3_f32 v148, v148, v92, v93
	s_waitcnt lgkmcnt(4)
	v_mfma_f32_32x32x16_bf16 v[16:31], v[220:223], v[232:235], v[16:31]
	v_max3_f32 v148, v148, v94, v95
	v_max3_f32 v148, v148, v64, v65
	v_max3_f32 v148, v148, v66, v67
	v_max3_f32 v148, v148, v68, v69
	v_max3_f32 v148, v148, v70, v71
	v_max3_f32 v148, v148, v72, v73
	v_max3_f32 v148, v148, v74, v75
	v_max3_f32 v148, v148, v76, v77
	s_waitcnt lgkmcnt(2)
	v_mfma_f32_32x32x16_bf16 v[16:31], v[224:227], v[236:239], v[16:31]
	v_max3_f32 v148, v148, v78, v79
	v_mov_b32_e32 v149, v148
	s_nop 1
	v_permlane32_swap_b32_e32 v148, v149
	v_max_f32_e32 v149, v149, v149
	v_max_f32_e32 v148, v148, v148
	v_max_f32_e32 v148, v148, v149
	v_sub_f32_e32 v149, v148, v153
	v_cmp_ge_f32_e32 vcc, s90, v149
	v_max_f32_e32 v149, v153, v153
	v_max_f32_e32 v149, v149, v148
	s_waitcnt lgkmcnt(0)
	v_mfma_f32_32x32x16_bf16 v[16:31], v[228:231], v[248:251], v[16:31]
	v_sub_f32_e32 v148, v153, v149
	v_mul_f32_e32 v148, 0x3dd53b94, v148
	v_exp_f32_e32 v148, v148
	s_cmp_eq_u64 vcc, exec
	s_cselect_b64 s[6:7], -1, 0
	s_barrier
	s_waitcnt vmcnt(0)
	v_cndmask_b32_e64 v148, v148, 1.0, s[6:7]
	v_cmp_gt_f32_e32 vcc, 1.0, v148
	s_waitcnt vmcnt(4)
	ds_write_b128 v185, v[128:131] offset:16384
	s_waitcnt vmcnt(2)
	ds_write_b128 v186, v[140:143] offset:16384
	s_waitcnt vmcnt(1)
	s_waitcnt vmcnt(0)
	ds_write_b128 v208, v[144:147]
	s_cbranch_vccz .LBB0_569
	s_and_saveexec_b64 s[0:1], s[4:5]
	ds_write_b32 v178, v148 offset:128
	s_or_b64 exec, exec, s[0:1]
	s_waitcnt lgkmcnt(0)
	v_add_u32_e32 v140, v157, v160
	ds_read_b128 v[128:131], v140 offset:224
	ds_read_b128 v[132:135], v140 offset:192
	ds_read_b128 v[136:139], v140 offset:160
	ds_read_b128 v[140:143], v140 offset:128
	s_waitcnt lgkmcnt(3)
	v_pk_mul_f32 v[12:13], v[12:13], v[128:129]
	s_waitcnt lgkmcnt(2)
	v_pk_mul_f32 v[8:9], v[8:9], v[132:133]
	s_waitcnt lgkmcnt(1)
	v_pk_mul_f32 v[4:5], v[4:5], v[136:137]
	v_pk_mul_f32 v[14:15], v[14:15], v[130:131]
	v_pk_mul_f32 v[10:11], v[10:11], v[134:135]
	v_pk_mul_f32 v[6:7], v[6:7], v[138:139]
	s_waitcnt lgkmcnt(0)
	v_pk_mul_f32 v[2:3], v[2:3], v[142:143]
	v_pk_mul_f32 v[0:1], v[0:1], v[140:141]
	v_pk_mul_f32 v[60:61], v[60:61], v[128:129]
	v_pk_mul_f32 v[56:57], v[56:57], v[132:133]
	v_pk_mul_f32 v[52:53], v[52:53], v[136:137]
	v_pk_mul_f32 v[62:63], v[62:63], v[130:131]
	v_pk_mul_f32 v[58:59], v[58:59], v[134:135]
	v_pk_mul_f32 v[54:55], v[54:55], v[138:139]
	v_pk_mul_f32 v[50:51], v[50:51], v[142:143]
	v_pk_mul_f32 v[48:49], v[48:49], v[140:141]
	v_pk_mul_f32 v[44:45], v[44:45], v[128:129]
	v_pk_mul_f32 v[40:41], v[40:41], v[132:133]
	v_pk_mul_f32 v[36:37], v[36:37], v[136:137]
	v_pk_mul_f32 v[46:47], v[46:47], v[130:131]
	v_pk_mul_f32 v[42:43], v[42:43], v[134:135]
	v_pk_mul_f32 v[38:39], v[38:39], v[138:139]
	v_pk_mul_f32 v[34:35], v[34:35], v[142:143]
	v_pk_mul_f32 v[32:33], v[32:33], v[140:141]
	v_pk_mul_f32 v[28:29], v[28:29], v[128:129]
	v_pk_mul_f32 v[24:25], v[24:25], v[132:133]
	v_pk_mul_f32 v[20:21], v[20:21], v[136:137]
	v_pk_mul_f32 v[30:31], v[30:31], v[130:131]
	v_pk_mul_f32 v[26:27], v[26:27], v[134:135]
	v_pk_mul_f32 v[22:23], v[22:23], v[138:139]
	v_pk_mul_f32 v[18:19], v[18:19], v[142:143]
	v_pk_mul_f32 v[16:17], v[16:17], v[140:141]
